# phase 8 rebalance (3/3 tiles per workgroup with release/acquire flag handoff), same as previous but using compiler-dead SGPRs instead of s98-s101
# speedup vs baseline: 1.0098x; 1.0049x over previous
.LBB0_1548:
	s_add_i32 s0, s0, 1
	s_waitcnt vmcnt(0)
	s_barrier
	s_cmp_eq_u32 s0, 5
	s_cbranch_scc0 .Lmy_p8_nosig
	s_cmp_lt_u32 s74, 0x80
	s_cbranch_scc0 .Lmy_p8_nosig
	v_cmp_eq_u32_e32 vcc, 0, v202
	s_and_saveexec_b64 s[2:3], vcc
	s_cbranch_execz .Lmy_p8_sigdone
	buffer_wbl2 sc1
	s_waitcnt vmcnt(0)
	v_readlane_b32 s8, v253, 2
	v_readlane_b32 s9, v253, 3
	s_lshl_b32 s4, s74, 2
	s_add_i32 s4, s4, 0x80000
	v_mov_b32_e32 v242, s4
	v_mov_b32_e32 v243, 1
	s_nop 4
	global_store_dword v242, v243, s[8:9] sc1
	s_waitcnt vmcnt(0)
.Lmy_p8_sigdone:
	s_or_b64 exec, exec, s[2:3]
.Lmy_p8_nosig:
	s_cmp_lt_u32 s0, s24
	s_cbranch_scc0 .LBB0_1439

.LBB0_1607:
	s_add_i32 s26, s26, 1
	s_mul_i32 s4, s26, s41
	s_mul_hi_u32 s5, s26, s78
	s_add_i32 s5, s5, s4
	s_mul_i32 s4, s26, s78
	s_add_u32 s4, s4, s33
	s_addc_u32 s5, s5, s91
	s_cmp_lg_u32 s66, 4
	s_cbranch_scc1 .Lmy_p8_map_done
	s_movk_i32 s18, 0x80
	s_cmp_lt_i32 s33, 0x80
	s_cbranch_scc1 .Lmy_p8_pos
	s_movk_i32 s18, 0xff80
.Lmy_p8_pos:
	s_ashr_i32 s19, s18, 31
	s_add_u32 s4, s4, s18
	s_addc_u32 s5, s5, s19

.LBB0_1632:
	s_andn2_b64 vcc, exec, s[6:7]
	s_cbranch_vccnz .LBB0_1634
	s_cmp_eq_u32 s26, 2
	s_cbranch_scc0 .Lmy_p8_nowait
	v_cmp_eq_u32_e32 vcc, 0, v202
	s_and_saveexec_b64 s[10:11], vcc
	s_cbranch_execz .Lmy_p8_waited
	v_readlane_b32 s8, v253, 2
	v_readlane_b32 s9, v253, 3
	s_sub_i32 s6, s74, 0x80
	s_lshl_b32 s6, s6, 2
	s_add_i32 s6, s6, 0x80000
	v_mov_b32_e32 v242, s6
	s_mov_b32 s7, 0x100000
	s_nop 4
.Lmy_p8_poll:
	global_load_dword v243, v242, s[8:9] sc1
	s_waitcnt vmcnt(0)
	v_cmp_ne_u32_e32 vcc, 0, v243
	s_cbranch_vccnz .Lmy_p8_pollok
	s_sleep 1
	s_sub_u32 s7, s7, 1
	s_cmp_lg_u32 s7, 0
	s_cbranch_scc1 .Lmy_p8_poll

.Lmy_p8_waited:
	s_or_b64 exec, exec, s[10:11]
	s_barrier
